# SWA tile loop: 16 exec-masked bias LDS lookups de-serialised (reads hoisted and issued together, one wait)
# speedup vs baseline: 1.0077x; 1.0077x over previous
.LBB0_1413:
	s_and_b32 s24, s24, 1
	s_cmp_gt_i32 s22, s20
	s_cselect_b64 s[6:7], -1, 0
	s_add_i32 s25, s22, 63
	s_cmp_lt_i32 s25, s21
	s_cselect_b64 s[28:29], -1, 0
	s_or_b64 s[6:7], s[6:7], s[28:29]
	s_and_b64 vcc, exec, s[6:7]
	s_cbranch_vccnz .LBB0_1447
	s_mul_i32 s6, s24, 0x2400
	v_add_u32_e32 v118, s6, v110
	ds_read_b128 v[34:37], v118 offset:4608
	ds_read_b128 v[38:41], v118
	ds_read_b128 v[120:123], v118 offset:32
	ds_read_b128 v[124:127], v118 offset:4640
	s_waitcnt lgkmcnt(2)
	v_mfma_f32_32x32x16_bf16 v[50:65], v[38:41], v[66:69], 0
	v_mfma_f32_32x32x16_bf16 v[34:49], v[34:37], v[66:69], 0
	s_waitcnt lgkmcnt(1)
	v_mfma_f32_32x32x16_bf16 v[50:65], v[120:123], v[70:73], v[50:65]
	s_waitcnt lgkmcnt(0)
	v_mfma_f32_32x32x16_bf16 v[34:49], v[124:127], v[70:73], v[34:49]
	ds_read_b128 v[120:123], v118 offset:64
	ds_read_b128 v[124:127], v118 offset:4672
	s_waitcnt lgkmcnt(1)
	v_mfma_f32_32x32x16_bf16 v[50:65], v[120:123], v[74:77], v[50:65]
	s_waitcnt lgkmcnt(0)
	v_mfma_f32_32x32x16_bf16 v[34:49], v[124:127], v[74:77], v[34:49]
	ds_read_b128 v[120:123], v118 offset:96
	ds_read_b128 v[124:127], v118 offset:4704
	ds_read_b32 v142, v116 offset:108
	ds_read_b32 v143, v116 offset:104
	ds_read_b32 v144, v116 offset:100
	ds_read_b32 v145, v116 offset:96
	ds_read_b32 v146, v116 offset:76
	ds_read_b32 v147, v116 offset:72
	ds_read_b32 v148, v116 offset:68
	ds_read_b32 v149, v116 offset:64
	ds_read_b32 v150, v116 offset:44
	ds_read_b32 v151, v116 offset:40
	ds_read_b32 v152, v116 offset:36
	ds_read_b32 v153, v116 offset:32
	ds_read_b32 v154, v116 offset:12
	ds_read_b32 v155, v116 offset:8
	ds_read_b32 v156, v116 offset:4
	ds_read_b32 v157, v116
	s_waitcnt lgkmcnt(1)
	v_mfma_f32_32x32x16_bf16 v[50:65], v[120:123], v[78:81], v[50:65]
	v_add_u32_e32 v121, 27, v101
	v_and_b32_e32 v121, 0x7f, v121
	v_lshl_add_u32 v121, v121, 2, 0
	v_add_u32_e32 v120, 0xffffffbb, v101
	v_cmp_gt_u32_e32 vcc, s91, v120
	v_mov_b32_e32 v120, 0xff800000
	s_waitcnt lgkmcnt(0)
	v_mfma_f32_32x32x16_bf16 v[34:49], v[124:127], v[78:81], v[34:49]
	ds_read_b32 v125, v121 offset:36864
	v_mov_b32_e32 v121, 0xff800000
	s_nop 1
	s_and_saveexec_b64 s[6:7], vcc
	s_cbranch_execz .LBB0_1416
	v_add_f32_e32 v121, v50, v142
.LBB0_1416:
	s_or_b64 exec, exec, s[6:7]
	v_add_u32_e32 v50, 26, v101
	v_and_b32_e32 v50, 0x7f, v50
	v_lshl_add_u32 v50, v50, 2, 0
	ds_read_b32 v126, v50 offset:36864
	v_add_u32_e32 v50, 0xffffffba, v101
	v_cmp_gt_u32_e32 vcc, s91, v50
	s_and_saveexec_b64 s[6:7], vcc
	s_cbranch_execz .LBB0_1418
	v_add_f32_e32 v120, v51, v143
.LBB0_1418:
	s_or_b64 exec, exec, s[6:7]
	v_add_u32_e32 v50, 25, v101
	v_and_b32_e32 v50, 0x7f, v50
	v_lshl_add_u32 v50, v50, 2, 0
	ds_read_b32 v51, v50 offset:36864
	v_add_u32_e32 v50, 0xffffffb9, v101
	v_cmp_gt_u32_e32 vcc, s91, v50
	v_mov_b32_e32 v50, 0xff800000
	v_mov_b32_e32 v122, 0xff800000
	s_and_saveexec_b64 s[6:7], vcc
	s_cbranch_execz .LBB0_1420
	v_add_f32_e32 v122, v52, v144
.LBB0_1420:
	s_or_b64 exec, exec, s[6:7]
	v_add_u32_e32 v52, 24, v101
	v_and_b32_e32 v52, 0x7f, v52
	v_lshl_add_u32 v52, v52, 2, 0
	ds_read_b32 v127, v52 offset:36864
	v_add_u32_e32 v52, 0xffffffb8, v101
	v_cmp_gt_u32_e32 vcc, s91, v52
	s_and_saveexec_b64 s[6:7], vcc
	s_cbranch_execz .LBB0_1422
	v_add_f32_e32 v50, v53, v145
.LBB0_1422:
	s_or_b64 exec, exec, s[6:7]
	v_add_u32_e32 v52, 19, v101
	v_and_b32_e32 v52, 0x7f, v52
	v_lshl_add_u32 v52, v52, 2, 0
	ds_read_b32 v128, v52 offset:36864
	v_add_u32_e32 v52, 0xffffffb3, v101
	v_cmp_gt_u32_e32 vcc, s91, v52
	v_mov_b32_e32 v52, 0xff800000
	v_mov_b32_e32 v123, 0xff800000
	s_and_saveexec_b64 s[6:7], vcc
	s_cbranch_execz .LBB0_1424
	v_add_f32_e32 v123, v54, v146
.LBB0_1424:
	s_or_b64 exec, exec, s[6:7]
	v_add_u32_e32 v53, 18, v101
	v_and_b32_e32 v53, 0x7f, v53
	v_lshl_add_u32 v53, v53, 2, 0
	ds_read_b32 v129, v53 offset:36864
	v_add_u32_e32 v53, 0xffffffb2, v101
	v_cmp_gt_u32_e32 vcc, s91, v53
	s_and_saveexec_b64 s[6:7], vcc
	s_cbranch_execz .LBB0_1426
	v_add_f32_e32 v52, v55, v147
.LBB0_1426:
	s_or_b64 exec, exec, s[6:7]
	v_add_u32_e32 v53, 17, v101
	v_and_b32_e32 v53, 0x7f, v53
	v_lshl_add_u32 v53, v53, 2, 0
	ds_read_b32 v130, v53 offset:36864
	v_add_u32_e32 v53, 0xffffffb1, v101
	v_cmp_gt_u32_e32 vcc, s91, v53
	v_mov_b32_e32 v53, 0xff800000
	v_mov_b32_e32 v124, 0xff800000
	s_and_saveexec_b64 s[6:7], vcc
	s_cbranch_execz .LBB0_1428
	v_add_f32_e32 v124, v56, v148
.LBB0_1428:
	s_or_b64 exec, exec, s[6:7]
	v_add_u32_e32 v54, 16, v101
	v_and_b32_e32 v54, 0x7f, v54
	v_lshl_add_u32 v54, v54, 2, 0
	ds_read_b32 v131, v54 offset:36864
	v_add_u32_e32 v54, 0xffffffb0, v101
	v_cmp_gt_u32_e32 vcc, s91, v54
	s_and_saveexec_b64 s[6:7], vcc
	s_cbranch_execz .LBB0_1430
	v_add_f32_e32 v53, v57, v149
.LBB0_1430:
	s_or_b64 exec, exec, s[6:7]
	v_add_u32_e32 v54, 11, v101
	v_and_b32_e32 v54, 0x7f, v54
	v_lshl_add_u32 v54, v54, 2, 0
	ds_read_b32 v132, v54 offset:36864
	v_add_u32_e32 v54, 0xffffffab, v101
	v_cmp_gt_u32_e32 vcc, s91, v54
	v_mov_b32_e32 v54, 0xff800000
	v_mov_b32_e32 v57, 0xff800000
	s_and_saveexec_b64 s[6:7], vcc
	s_cbranch_execz .LBB0_1432
	v_add_f32_e32 v57, v58, v150
.LBB0_1432:
	s_or_b64 exec, exec, s[6:7]
	v_add_u32_e32 v55, 10, v101
	v_and_b32_e32 v55, 0x7f, v55
	v_lshl_add_u32 v55, v55, 2, 0
	ds_read_b32 v133, v55 offset:36864
	v_add_u32_e32 v55, 0xffffffaa, v101
	v_cmp_gt_u32_e32 vcc, s91, v55
	s_and_saveexec_b64 s[6:7], vcc
	s_cbranch_execz .LBB0_1434
	v_add_f32_e32 v54, v59, v151
.LBB0_1434:
	s_or_b64 exec, exec, s[6:7]
	v_add_u32_e32 v55, 9, v101
	v_and_b32_e32 v55, 0x7f, v55
	v_lshl_add_u32 v55, v55, 2, 0
	ds_read_b32 v134, v55 offset:36864
	v_add_u32_e32 v55, 0xffffffa9, v101
	v_cmp_gt_u32_e32 vcc, s91, v55
	v_mov_b32_e32 v55, 0xff800000
	v_mov_b32_e32 v59, 0xff800000
	s_and_saveexec_b64 s[6:7], vcc
	s_cbranch_execz .LBB0_1436
	v_add_f32_e32 v59, v60, v152
.LBB0_1436:
	s_or_b64 exec, exec, s[6:7]
	v_add_u32_e32 v56, 8, v101
	v_and_b32_e32 v56, 0x7f, v56
	v_lshl_add_u32 v56, v56, 2, 0
	ds_read_b32 v135, v56 offset:36864
	v_add_u32_e32 v56, 0xffffffa8, v101
	v_cmp_gt_u32_e32 vcc, s91, v56
	s_and_saveexec_b64 s[6:7], vcc
	s_cbranch_execz .LBB0_1438
	v_add_f32_e32 v55, v61, v153
.LBB0_1438:
	s_or_b64 exec, exec, s[6:7]
	v_add_u32_e32 v56, 3, v101
	v_and_b32_e32 v56, 0x7f, v56
	v_lshl_add_u32 v56, v56, 2, 0
	ds_read_b32 v136, v56 offset:36864
	v_add_u32_e32 v56, 0xffffffa3, v101
	v_cmp_gt_u32_e32 vcc, s91, v56
	v_mov_b32_e32 v56, 0xff800000
	v_mov_b32_e32 v60, 0xff800000
	s_and_saveexec_b64 s[6:7], vcc
	s_cbranch_execz .LBB0_1440
	v_add_f32_e32 v60, v62, v154
.LBB0_1440:
	s_or_b64 exec, exec, s[6:7]
	v_add_u32_e32 v58, 2, v101
	v_and_b32_e32 v58, 0x7f, v58
	v_lshl_add_u32 v58, v58, 2, 0
	ds_read_b32 v137, v58 offset:36864
	v_add_u32_e32 v58, 0xffffffa2, v101
	v_cmp_gt_u32_e32 vcc, s91, v58
	s_and_saveexec_b64 s[6:7], vcc
	s_cbranch_execz .LBB0_1442
	v_add_f32_e32 v56, v63, v155
.LBB0_1442:
	s_or_b64 exec, exec, s[6:7]
	v_add_u32_e32 v58, 1, v101
	v_and_b32_e32 v58, 0x7f, v58
	v_lshl_add_u32 v58, v58, 2, 0
	ds_read_b32 v63, v58 offset:36864
	v_add_u32_e32 v58, 0xffffffa1, v101
	v_cmp_gt_u32_e32 vcc, s91, v58
	v_mov_b32_e32 v58, 0xff800000
	v_mov_b32_e32 v61, 0xff800000
	s_and_saveexec_b64 s[6:7], vcc
	s_cbranch_execz .LBB0_1444
	v_add_f32_e32 v61, v64, v156
.LBB0_1444:
	s_or_b64 exec, exec, s[6:7]
	v_and_b32_e32 v62, 0x7f, v101
	v_lshl_add_u32 v62, v62, 2, 0
	ds_read_b32 v62, v62 offset:36864
	v_add_u32_e32 v64, 0xffffffa0, v101
	v_cmp_gt_u32_e32 vcc, s91, v64
	s_and_saveexec_b64 s[6:7], vcc
	s_cbranch_execz .LBB0_1446
	v_add_f32_e32 v58, v65, v157
